# SwiGLU epilogue hand-scheduled with batched trans ops and v_pk f32 math, ACT stores write-through sc1, accumulator zeroing via v_mov_b64
# speedup vs baseline: 1.0093x; 1.0093x over previous
.LBB0_69:
	s_add_i32 m0, s3, 0x18000
	v_lshl_add_u64 v[0:1], v[0:1], 0, s[66:67]
	s_waitcnt vmcnt(4)
	s_barrier
	global_load_lds_dwordx4 v[0:1], off
	v_lshl_add_u64 v[0:1], v[2:3], 0, s[66:67]
	s_add_i32 m0, s3, 0x1a000
	s_add_i32 s30, s3, 0x8000
	global_load_lds_dwordx4 v[0:1], off
	v_lshl_add_u64 v[0:1], v[4:5], 0, s[66:67]
	s_mov_b32 m0, s30
	s_add_i32 s31, s3, 0xa000
	global_load_lds_dwordx4 v[0:1], off
	v_lshl_add_u64 v[0:1], v[6:7], 0, s[66:67]
	s_mov_b32 m0, s31
	v_and_b32_e32 v19, 15, v15
	global_load_lds_dwordx4 v[0:1], off
	s_add_i32 m0, s3, 0x1c000
	v_lshl_add_u64 v[0:1], v[8:9], 0, s[66:67]
	global_load_lds_dwordx4 v[0:1], off
	v_lshl_add_u64 v[0:1], v[10:11], 0, s[66:67]
	s_add_i32 m0, s3, 0x1e000
	v_and_b32_e32 v20, 48, v15
	global_load_lds_dwordx4 v[0:1], off
	v_lshlrev_b32_e32 v19, 6, v19
	v_lshlrev_b32_e32 v15, 2, v15
	s_lshr_b32 s29, s19, 6
	v_or_b32_e32 v21, v19, v20
	s_lshl_b32 s19, s23, 13
	v_and_b32_e32 v15, 32, v15
	v_bitop3_b32 v19, v19, v15, v20 bitop3:0x36
	v_bitop3_b32 v15, v21, s19, v15 bitop3:0xde
	s_lshl_b32 s19, s22, 12
	s_and_b32 s19, s19, 0x3000
	s_add_i32 s34, s29, -2
	s_add_u32 s16, s18, s16
	s_addc_u32 s17, 0, s17
	s_add_u32 s12, s16, s12
	s_addc_u32 s13, s17, s13
	s_add_u32 s12, s12, s25
	s_addc_u32 s13, s13, 0
	s_add_u32 s12, s80, s12
	s_addc_u32 s13, s81, s13
	v_add_u32_e32 v0, v16, v17
	s_add_u32 s12, s12, 0x80
	v_add_lshl_u32 v0, v0, v18, 1
	v_mov_b32_e32 v1, v133
	s_addc_u32 s13, s13, 0
	v_lshl_add_u64 v[130:131], s[12:13], 0, v[0:1]
	v_add_u32_e32 v0, v12, v13
	s_waitcnt vmcnt(6)
	v_add_lshl_u32 v0, v0, v14, 1
	v_lshl_add_u64 v[150:151], s[12:13], 0, v[0:1]
	v_mov_b32_e32 v0, 0
	v_or_b32_e32 v152, s19, v19
	s_mov_b32 s18, 0
	s_mov_b64 s[12:13], 0
	v_add_u32_e32 v153, 0, v15
	v_mov_b32_e32 v1, v0
	v_mov_b64_e32 v[2:3], 0
	v_mov_b64_e32 v[4:5], 0
	v_mov_b64_e32 v[6:7], 0
	v_mov_b64_e32 v[8:9], 0
	v_mov_b64_e32 v[10:11], 0
	v_mov_b64_e32 v[12:13], 0
	v_mov_b64_e32 v[14:15], 0
	v_mov_b64_e32 v[16:17], 0
	v_mov_b64_e32 v[18:19], 0
	v_mov_b64_e32 v[20:21], 0
	v_mov_b64_e32 v[22:23], 0
	v_mov_b64_e32 v[24:25], 0
	v_mov_b64_e32 v[26:27], 0
	v_mov_b64_e32 v[28:29], 0
	v_mov_b64_e32 v[30:31], 0
	v_mov_b64_e32 v[32:33], 0
	v_mov_b64_e32 v[34:35], 0
	v_mov_b64_e32 v[36:37], 0
	v_mov_b64_e32 v[38:39], 0
	v_mov_b64_e32 v[40:41], 0
	v_mov_b64_e32 v[42:43], 0
	v_mov_b64_e32 v[44:45], 0
	v_mov_b64_e32 v[46:47], 0
	v_mov_b64_e32 v[48:49], 0
	v_mov_b64_e32 v[50:51], 0
	v_mov_b64_e32 v[52:53], 0
	v_mov_b64_e32 v[54:55], 0
	v_mov_b64_e32 v[56:57], 0
	v_mov_b64_e32 v[58:59], 0
	v_mov_b64_e32 v[60:61], 0
	v_mov_b64_e32 v[62:63], 0
	v_mov_b64_e32 v[64:65], 0
	v_mov_b64_e32 v[66:67], 0
	v_mov_b64_e32 v[68:69], 0
	v_mov_b64_e32 v[70:71], 0
	v_mov_b64_e32 v[72:73], 0
	v_mov_b64_e32 v[74:75], 0
	v_mov_b64_e32 v[76:77], 0
	v_mov_b64_e32 v[78:79], 0
	v_mov_b64_e32 v[80:81], 0
	v_mov_b64_e32 v[82:83], 0
	v_mov_b64_e32 v[84:85], 0
	v_mov_b64_e32 v[86:87], 0
	v_mov_b64_e32 v[88:89], 0
	v_mov_b64_e32 v[90:91], 0
	v_mov_b64_e32 v[92:93], 0
	v_mov_b64_e32 v[94:95], 0
	v_mov_b64_e32 v[96:97], 0
	v_mov_b64_e32 v[98:99], 0
	v_mov_b64_e32 v[100:101], 0
	v_mov_b64_e32 v[102:103], 0
	v_mov_b64_e32 v[104:105], 0
	v_mov_b64_e32 v[106:107], 0
	v_mov_b64_e32 v[108:109], 0
	v_mov_b64_e32 v[110:111], 0
	v_mov_b64_e32 v[112:113], 0
	v_mov_b64_e32 v[114:115], 0
	v_mov_b64_e32 v[116:117], 0
	v_mov_b64_e32 v[118:119], 0
	v_mov_b64_e32 v[120:121], 0
	v_mov_b64_e32 v[122:123], 0
	v_mov_b64_e32 v[124:125], 0
	v_mov_b64_e32 v[126:127], 0
	s_barrier

.LBB0_144:
	s_ashr_i32 s19, s18, 31
	v_cmp_lt_i64_e32 vcc, s[10:11], v[140:141]
	s_lshl_b64 s[10:11], s[18:19], 19
	s_add_u32 s22, s86, s10
	s_addc_u32 s23, s87, s11
	s_and_b64 s[10:11], vcc, exec
	s_cselect_b32 s9, s23, s3
	s_cselect_b32 s12, s22, s2
	s_ashr_i32 s17, s16, 31
	s_lshl_b64 s[10:11], s[16:17], 19
	s_add_u32 s24, s41, s10
	s_addc_u32 s25, s14, s11
	s_and_b64 s[10:11], vcc, exec
	s_cselect_b32 s13, s25, s7
	s_cselect_b32 s17, s24, s6
	s_add_u32 s2, s2, 0x40080
	s_addc_u32 s3, s3, 0
	s_add_u32 s19, s6, 0x100
	v_mov_b32_e32 v0, 0
	s_addc_u32 s27, s7, 0
	s_waitcnt lgkmcnt(0)
	s_mov_b32 s28, -2
	v_mov_b32_e32 v1, v0
	v_mov_b64_e32 v[2:3], 0
	v_mov_b64_e32 v[4:5], 0
	v_mov_b64_e32 v[6:7], 0
	v_mov_b64_e32 v[8:9], 0
	v_mov_b64_e32 v[10:11], 0
	v_mov_b64_e32 v[12:13], 0
	v_mov_b64_e32 v[14:15], 0
	v_mov_b64_e32 v[16:17], 0
	v_mov_b64_e32 v[18:19], 0
	v_mov_b64_e32 v[20:21], 0
	v_mov_b64_e32 v[22:23], 0
	v_mov_b64_e32 v[24:25], 0
	v_mov_b64_e32 v[26:27], 0
	v_mov_b64_e32 v[28:29], 0
	v_mov_b64_e32 v[30:31], 0
	v_mov_b64_e32 v[32:33], 0
	v_mov_b64_e32 v[34:35], 0
	v_mov_b64_e32 v[36:37], 0
	v_mov_b64_e32 v[38:39], 0
	v_mov_b64_e32 v[40:41], 0
	v_mov_b64_e32 v[42:43], 0
	v_mov_b64_e32 v[44:45], 0
	v_mov_b64_e32 v[46:47], 0
	v_mov_b64_e32 v[48:49], 0
	v_mov_b64_e32 v[50:51], 0
	v_mov_b64_e32 v[52:53], 0
	v_mov_b64_e32 v[54:55], 0
	v_mov_b64_e32 v[56:57], 0
	v_mov_b64_e32 v[58:59], 0
	v_mov_b64_e32 v[60:61], 0
	v_mov_b64_e32 v[62:63], 0
	v_mov_b64_e32 v[64:65], 0
	v_mov_b64_e32 v[66:67], 0
	v_mov_b64_e32 v[68:69], 0
	v_mov_b64_e32 v[70:71], 0
	v_mov_b64_e32 v[72:73], 0
	v_mov_b64_e32 v[74:75], 0
	v_mov_b64_e32 v[76:77], 0
	v_mov_b64_e32 v[78:79], 0
	v_mov_b64_e32 v[80:81], 0
	v_mov_b64_e32 v[82:83], 0
	v_mov_b64_e32 v[84:85], 0
	v_mov_b64_e32 v[86:87], 0
	v_mov_b64_e32 v[88:89], 0
	v_mov_b64_e32 v[90:91], 0
	v_mov_b64_e32 v[92:93], 0
	v_mov_b64_e32 v[94:95], 0
	v_mov_b64_e32 v[96:97], 0
	v_mov_b64_e32 v[98:99], 0
	v_mov_b64_e32 v[100:101], 0
	v_mov_b64_e32 v[102:103], 0
	v_mov_b64_e32 v[104:105], 0
	v_mov_b64_e32 v[106:107], 0
	v_mov_b64_e32 v[108:109], 0
	v_mov_b64_e32 v[110:111], 0
	v_mov_b64_e32 v[112:113], 0
	v_mov_b64_e32 v[114:115], 0
	v_mov_b64_e32 v[116:117], 0
	v_mov_b64_e32 v[118:119], 0
	v_mov_b64_e32 v[120:121], 0
	v_mov_b64_e32 v[122:123], 0
	v_mov_b64_e32 v[124:125], 0
	v_mov_b64_e32 v[126:127], 0

.LBB0_1103:
	s_ashr_i32 s9, s8, 31
	v_cmp_lt_i64_e32 vcc, s[10:11], v[144:145]
	s_lshl_b64 s[10:11], s[8:9], 19
	s_add_u32 s10, s15, s10
	s_addc_u32 s11, s26, s11
	s_and_b64 s[12:13], vcc, exec
	s_cselect_b32 s9, s11, s19
	s_cselect_b32 s42, s10, s18
	s_ashr_i32 s7, s6, 31
	s_lshl_b64 s[12:13], s[6:7], 19
	s_add_u32 s12, s27, s12
	s_addc_u32 s13, s28, s13
	s_and_b64 s[24:25], vcc, exec
	s_cselect_b32 s7, s13, s23
	s_cselect_b32 s43, s12, s22
	s_add_u32 s18, s18, 0x40080
	s_addc_u32 s19, s19, 0
	s_add_u32 s44, s22, 0x100
	v_mov_b32_e32 v0, 0
	s_addc_u32 s45, s23, 0
	s_mov_b32 s46, -2
	v_mov_b32_e32 v1, v0
	v_mov_b64_e32 v[2:3], 0
	v_mov_b64_e32 v[4:5], 0
	v_mov_b64_e32 v[6:7], 0
	v_mov_b64_e32 v[8:9], 0
	v_mov_b64_e32 v[10:11], 0
	v_mov_b64_e32 v[12:13], 0
	v_mov_b64_e32 v[14:15], 0
	v_mov_b64_e32 v[16:17], 0
	v_mov_b64_e32 v[18:19], 0
	v_mov_b64_e32 v[20:21], 0
	v_mov_b64_e32 v[22:23], 0
	v_mov_b64_e32 v[24:25], 0
	v_mov_b64_e32 v[26:27], 0
	v_mov_b64_e32 v[28:29], 0
	v_mov_b64_e32 v[30:31], 0
	v_mov_b64_e32 v[32:33], 0
	v_mov_b64_e32 v[34:35], 0
	v_mov_b64_e32 v[36:37], 0
	v_mov_b64_e32 v[38:39], 0
	v_mov_b64_e32 v[40:41], 0
	v_mov_b64_e32 v[42:43], 0
	v_mov_b64_e32 v[44:45], 0
	v_mov_b64_e32 v[46:47], 0
	v_mov_b64_e32 v[48:49], 0
	v_mov_b64_e32 v[50:51], 0
	v_mov_b64_e32 v[52:53], 0
	v_mov_b64_e32 v[54:55], 0
	v_mov_b64_e32 v[56:57], 0
	v_mov_b64_e32 v[58:59], 0
	v_mov_b64_e32 v[60:61], 0
	v_mov_b64_e32 v[62:63], 0
	v_mov_b64_e32 v[64:65], 0
	v_mov_b64_e32 v[66:67], 0
	v_mov_b64_e32 v[68:69], 0
	v_mov_b64_e32 v[70:71], 0
	v_mov_b64_e32 v[72:73], 0
	v_mov_b64_e32 v[74:75], 0
	v_mov_b64_e32 v[76:77], 0
	v_mov_b64_e32 v[78:79], 0
	v_mov_b64_e32 v[80:81], 0
	v_mov_b64_e32 v[82:83], 0
	v_mov_b64_e32 v[84:85], 0
	v_mov_b64_e32 v[86:87], 0
	v_mov_b64_e32 v[88:89], 0
	v_mov_b64_e32 v[90:91], 0
	v_mov_b64_e32 v[92:93], 0
	v_mov_b64_e32 v[94:95], 0
	v_mov_b64_e32 v[96:97], 0
	v_mov_b64_e32 v[98:99], 0
	v_mov_b64_e32 v[100:101], 0
	v_mov_b64_e32 v[102:103], 0
	v_mov_b64_e32 v[104:105], 0
	v_mov_b64_e32 v[106:107], 0
	v_mov_b64_e32 v[108:109], 0
	v_mov_b64_e32 v[110:111], 0
	v_mov_b64_e32 v[112:113], 0
	v_mov_b64_e32 v[114:115], 0
	v_mov_b64_e32 v[116:117], 0
	v_mov_b64_e32 v[118:119], 0
	v_mov_b64_e32 v[120:121], 0
	v_mov_b64_e32 v[122:123], 0
	v_mov_b64_e32 v[124:125], 0
	v_mov_b64_e32 v[126:127], 0
.LBB0_1104:
	s_add_u32 s22, s18, 0xfffc0080
	s_addc_u32 s23, s19, -1
	s_add_i32 s47, 0, 0x10000
	v_add_u32_e32 v152, s47, v154
	ds_read_b128 v[156:159], v152
	ds_read_b128 v[160:163], v152 offset:1024
	ds_read_b128 v[164:167], v152 offset:2048
	ds_read_b128 v[168:171], v152 offset:3072
	s_cmp_eq_u32 s46, 12
	s_cselect_b32 s25, s9, s23
	s_cselect_b32 s24, s42, s22
	s_cselect_b32 s23, s7, s45
	s_cselect_b32 s22, s43, s44
	v_lshl_add_u64 v[152:153], s[18:19], 0, v[130:131]
	s_add_i32 m0, s17, 0xc000
	ds_read_b128 v[172:175], v155
	ds_read_b128 v[180:183], v155 offset:2048
	ds_read_b128 v[188:191], v155 offset:4096
	ds_read_b128 v[220:223], v155 offset:6144
	ds_read_b128 v[176:179], v155 offset:1024
	ds_read_b128 v[184:187], v155 offset:3072
	ds_read_b128 v[216:219], v155 offset:5120
	ds_read_b128 v[224:227], v155 offset:7168
	global_load_lds_dwordx4 v[152:153], off
	v_lshl_add_u64 v[152:153], s[18:19], 0, v[150:151]
	s_add_i32 m0, s17, 0xe000
	s_nop 0
	global_load_lds_dwordx4 v[152:153], off
	s_waitcnt lgkmcnt(8)
	s_barrier
	s_waitcnt lgkmcnt(4)
	s_setprio 1
	v_mfma_f32_16x16x32_bf16 v[124:127], v[156:159], v[172:175], v[124:127]
	v_mfma_f32_16x16x32_bf16 v[120:123], v[164:167], v[172:175], v[120:123]
	v_mfma_f32_16x16x32_bf16 v[108:111], v[156:159], v[180:183], v[108:111]
	v_mfma_f32_16x16x32_bf16 v[104:107], v[164:167], v[180:183], v[104:107]
	v_mfma_f32_16x16x32_bf16 v[92:95], v[156:159], v[188:191], v[92:95]
	v_mfma_f32_16x16x32_bf16 v[88:91], v[164:167], v[188:191], v[88:91]
	v_mfma_f32_16x16x32_bf16 v[76:79], v[156:159], v[220:223], v[76:79]
	v_mfma_f32_16x16x32_bf16 v[72:75], v[164:167], v[220:223], v[72:75]
	s_waitcnt lgkmcnt(0)
	v_mfma_f32_16x16x32_bf16 v[124:127], v[160:163], v[176:179], v[124:127]
	v_mfma_f32_16x16x32_bf16 v[120:123], v[168:171], v[176:179], v[120:123]
	v_mfma_f32_16x16x32_bf16 v[108:111], v[160:163], v[184:187], v[108:111]
	v_mfma_f32_16x16x32_bf16 v[104:107], v[168:171], v[184:187], v[104:107]
	v_mfma_f32_16x16x32_bf16 v[92:95], v[160:163], v[216:219], v[92:95]
	v_mfma_f32_16x16x32_bf16 v[88:91], v[168:171], v[216:219], v[88:91]
	v_mfma_f32_16x16x32_bf16 v[76:79], v[160:163], v[224:227], v[76:79]
	v_mfma_f32_16x16x32_bf16 v[72:75], v[168:171], v[224:227], v[72:75]
	s_setprio 0
	s_barrier
	s_add_i32 s50, 0, 0x14000
	v_add_u32_e32 v152, s50, v154
	s_add_i32 s47, s47, s29
	ds_read_b128 v[228:231], v152
	ds_read_b128 v[236:239], v152 offset:2048
	ds_read_b128 v[232:235], v152 offset:1024
	ds_read_b128 v[240:243], v152 offset:3072
	v_lshl_add_u64 v[152:153], s[22:23], 0, v[132:133]
	s_mov_b32 m0, s47
	v_lshl_add_u64 v[244:245], s[22:23], 0, v[128:129]
	global_load_lds_dwordx4 v[152:153], off
	s_add_i32 m0, s47, 0x2000
	s_nop 0
	global_load_lds_dwordx4 v[244:245], off
	s_barrier
	s_waitcnt lgkmcnt(2)
	s_setprio 1
	v_mfma_f32_16x16x32_bf16 v[116:119], v[228:231], v[172:175], v[116:119]
	v_mfma_f32_16x16x32_bf16 v[112:115], v[236:239], v[172:175], v[112:115]
	v_mfma_f32_16x16x32_bf16 v[100:103], v[228:231], v[180:183], v[100:103]
	v_mfma_f32_16x16x32_bf16 v[96:99], v[236:239], v[180:183], v[96:99]
	v_mfma_f32_16x16x32_bf16 v[84:87], v[228:231], v[188:191], v[84:87]
	v_mfma_f32_16x16x32_bf16 v[80:83], v[236:239], v[188:191], v[80:83]
	v_mfma_f32_16x16x32_bf16 v[68:71], v[228:231], v[220:223], v[68:71]
	v_mfma_f32_16x16x32_bf16 v[64:67], v[236:239], v[220:223], v[64:67]
	s_waitcnt lgkmcnt(0)
	v_mfma_f32_16x16x32_bf16 v[116:119], v[232:235], v[176:179], v[116:119]
	v_mfma_f32_16x16x32_bf16 v[112:115], v[240:243], v[176:179], v[112:115]
	v_mfma_f32_16x16x32_bf16 v[100:103], v[232:235], v[184:187], v[100:103]
	v_mfma_f32_16x16x32_bf16 v[96:99], v[240:243], v[184:187], v[96:99]
	v_mfma_f32_16x16x32_bf16 v[84:87], v[232:235], v[216:219], v[84:87]
	v_mfma_f32_16x16x32_bf16 v[80:83], v[240:243], v[216:219], v[80:83]
	v_mfma_f32_16x16x32_bf16 v[68:71], v[232:235], v[224:227], v[68:71]
	v_mfma_f32_16x16x32_bf16 v[64:67], v[240:243], v[224:227], v[64:67]
	s_setprio 0
	s_mov_b32 m0, s17
	v_lshl_add_u64 v[246:247], s[24:25], 0, v[132:133]
	s_barrier
	ds_read_b128 v[172:175], v155 offset:16384
	ds_read_b128 v[180:183], v155 offset:18432
	ds_read_b128 v[188:191], v155 offset:20480
	ds_read_b128 v[220:223], v155 offset:22528
	ds_read_b128 v[176:179], v155 offset:17408
	ds_read_b128 v[184:187], v155 offset:19456
	ds_read_b128 v[216:219], v155 offset:21504
	ds_read_b128 v[224:227], v155 offset:23552
	global_load_lds_dwordx4 v[246:247], off
	v_lshl_add_u64 v[248:249], s[24:25], 0, v[128:129]
	s_mov_b32 m0, s31
	s_nop 0
	global_load_lds_dwordx4 v[248:249], off
	s_barrier
	s_waitcnt lgkmcnt(4)
	s_setprio 1
	v_mfma_f32_16x16x32_bf16 v[60:63], v[156:159], v[172:175], v[60:63]
	v_mfma_f32_16x16x32_bf16 v[56:59], v[164:167], v[172:175], v[56:59]
	v_mfma_f32_16x16x32_bf16 v[44:47], v[156:159], v[180:183], v[44:47]
	v_mfma_f32_16x16x32_bf16 v[40:43], v[164:167], v[180:183], v[40:43]
	v_mfma_f32_16x16x32_bf16 v[28:31], v[156:159], v[188:191], v[28:31]
	v_mfma_f32_16x16x32_bf16 v[24:27], v[164:167], v[188:191], v[24:27]
	v_mfma_f32_16x16x32_bf16 v[12:15], v[156:159], v[220:223], v[12:15]
	v_mfma_f32_16x16x32_bf16 v[8:11], v[164:167], v[220:223], v[8:11]
	s_waitcnt lgkmcnt(0)
	v_mfma_f32_16x16x32_bf16 v[60:63], v[160:163], v[176:179], v[60:63]
	v_mfma_f32_16x16x32_bf16 v[56:59], v[168:171], v[176:179], v[56:59]
	v_mfma_f32_16x16x32_bf16 v[44:47], v[160:163], v[184:187], v[44:47]
	v_mfma_f32_16x16x32_bf16 v[40:43], v[168:171], v[184:187], v[40:43]
	v_mfma_f32_16x16x32_bf16 v[28:31], v[160:163], v[216:219], v[28:31]
	v_mfma_f32_16x16x32_bf16 v[24:27], v[168:171], v[216:219], v[24:27]
	v_mfma_f32_16x16x32_bf16 v[12:15], v[160:163], v[224:227], v[12:15]
	v_mfma_f32_16x16x32_bf16 v[8:11], v[168:171], v[224:227], v[8:11]
	s_setprio 0
	s_barrier
	s_add_u32 s48, s22, 0x40000
	s_addc_u32 s49, s23, 0
	s_add_i32 s47, s50, s29
	v_lshl_add_u64 v[156:157], s[48:49], 0, v[132:133]
	s_mov_b32 m0, s47
	s_nop 0
	global_load_lds_dwordx4 v[156:157], off
	v_lshl_add_u64 v[156:157], s[48:49], 0, v[128:129]
	s_add_i32 m0, s47, 0x2000
	s_nop 0
	global_load_lds_dwordx4 v[156:157], off
	s_waitcnt vmcnt(6)
	s_barrier
	s_setprio 1
	v_mfma_f32_16x16x32_bf16 v[52:55], v[228:231], v[172:175], v[52:55]
	v_mfma_f32_16x16x32_bf16 v[48:51], v[236:239], v[172:175], v[48:51]
	v_mfma_f32_16x16x32_bf16 v[36:39], v[228:231], v[180:183], v[36:39]
	v_mfma_f32_16x16x32_bf16 v[32:35], v[236:239], v[180:183], v[32:35]
	v_mfma_f32_16x16x32_bf16 v[20:23], v[228:231], v[188:191], v[20:23]
	v_mfma_f32_16x16x32_bf16 v[16:19], v[236:239], v[188:191], v[16:19]
	v_mfma_f32_16x16x32_bf16 v[4:7], v[228:231], v[220:223], v[4:7]
	v_mfma_f32_16x16x32_bf16 v[0:3], v[236:239], v[220:223], v[0:3]
	v_mfma_f32_16x16x32_bf16 v[52:55], v[232:235], v[176:179], v[52:55]
	v_mfma_f32_16x16x32_bf16 v[48:51], v[240:243], v[176:179], v[48:51]
	v_mfma_f32_16x16x32_bf16 v[36:39], v[232:235], v[184:187], v[36:39]
	v_mfma_f32_16x16x32_bf16 v[32:35], v[240:243], v[184:187], v[32:35]
	v_mfma_f32_16x16x32_bf16 v[20:23], v[232:235], v[216:219], v[20:23]
	v_mfma_f32_16x16x32_bf16 v[16:19], v[240:243], v[216:219], v[16:19]
	v_mfma_f32_16x16x32_bf16 v[4:7], v[232:235], v[224:227], v[4:7]
	v_mfma_f32_16x16x32_bf16 v[0:3], v[240:243], v[224:227], v[0:3]
	s_setprio 0
	s_add_i32 s47, 0, 0x18000
	v_add_u32_e32 v168, s47, v154
	s_barrier
	ds_read_b128 v[156:159], v168
	ds_read_b128 v[160:163], v168 offset:1024
	ds_read_b128 v[164:167], v168 offset:2048
	ds_read_b128 v[168:171], v168 offset:3072
	s_add_u32 s24, s24, 0x40000
	s_addc_u32 s25, s25, 0
	s_mov_b32 m0, s34
	v_lshl_add_u64 v[228:229], s[24:25], 0, v[132:133]
	ds_read_b128 v[172:175], v155 offset:32768
	ds_read_b128 v[180:183], v155 offset:34816
	ds_read_b128 v[188:191], v155 offset:36864
	ds_read_b128 v[220:223], v155 offset:38912
	ds_read_b128 v[176:179], v155 offset:33792
	ds_read_b128 v[184:187], v155 offset:35840
	ds_read_b128 v[216:219], v155 offset:37888
	ds_read_b128 v[224:227], v155 offset:39936
	global_load_lds_dwordx4 v[228:229], off
	v_lshl_add_u64 v[228:229], s[24:25], 0, v[128:129]
	s_mov_b32 m0, s35
	s_nop 0
	global_load_lds_dwordx4 v[228:229], off
	s_waitcnt lgkmcnt(8)
	s_barrier
	s_waitcnt lgkmcnt(4)
	s_setprio 1
	v_mfma_f32_16x16x32_bf16 v[124:127], v[156:159], v[172:175], v[124:127]
	v_mfma_f32_16x16x32_bf16 v[120:123], v[164:167], v[172:175], v[120:123]
	v_mfma_f32_16x16x32_bf16 v[108:111], v[156:159], v[180:183], v[108:111]
	v_mfma_f32_16x16x32_bf16 v[104:107], v[164:167], v[180:183], v[104:107]
	v_mfma_f32_16x16x32_bf16 v[92:95], v[156:159], v[188:191], v[92:95]
	v_mfma_f32_16x16x32_bf16 v[88:91], v[164:167], v[188:191], v[88:91]
	v_mfma_f32_16x16x32_bf16 v[76:79], v[156:159], v[220:223], v[76:79]
	v_mfma_f32_16x16x32_bf16 v[72:75], v[164:167], v[220:223], v[72:75]
	s_waitcnt lgkmcnt(0)
	v_mfma_f32_16x16x32_bf16 v[124:127], v[160:163], v[176:179], v[124:127]
	v_mfma_f32_16x16x32_bf16 v[120:123], v[168:171], v[176:179], v[120:123]
	v_mfma_f32_16x16x32_bf16 v[108:111], v[160:163], v[184:187], v[108:111]
	v_mfma_f32_16x16x32_bf16 v[104:107], v[168:171], v[184:187], v[104:107]
	v_mfma_f32_16x16x32_bf16 v[92:95], v[160:163], v[216:219], v[92:95]
	v_mfma_f32_16x16x32_bf16 v[88:91], v[168:171], v[216:219], v[88:91]
	v_mfma_f32_16x16x32_bf16 v[76:79], v[160:163], v[224:227], v[76:79]
	v_mfma_f32_16x16x32_bf16 v[72:75], v[168:171], v[224:227], v[72:75]
	s_setprio 0
	s_barrier
	s_add_i32 s24, 0, 0x1c000
	s_add_i32 s25, s47, s29
	v_add_u32_e32 v200, s24, v154
	v_lshl_add_u64 v[152:153], v[152:153], 0, s[66:67]
	s_mov_b32 m0, s25
	ds_read_b128 v[228:231], v200
	ds_read_b128 v[236:239], v200 offset:2048
	ds_read_b128 v[232:235], v200 offset:1024
	ds_read_b128 v[240:243], v200 offset:3072
	global_load_lds_dwordx4 v[152:153], off
	v_lshl_add_u64 v[152:153], v[244:245], 0, s[66:67]
	s_add_i32 m0, s25, 0x2000
	s_nop 0
	global_load_lds_dwordx4 v[152:153], off
	s_barrier
	s_waitcnt lgkmcnt(2)
	s_setprio 1
	v_mfma_f32_16x16x32_bf16 v[116:119], v[228:231], v[172:175], v[116:119]
	v_mfma_f32_16x16x32_bf16 v[112:115], v[236:239], v[172:175], v[112:115]
	v_mfma_f32_16x16x32_bf16 v[100:103], v[228:231], v[180:183], v[100:103]
	v_mfma_f32_16x16x32_bf16 v[96:99], v[236:239], v[180:183], v[96:99]
	v_mfma_f32_16x16x32_bf16 v[84:87], v[228:231], v[188:191], v[84:87]
	v_mfma_f32_16x16x32_bf16 v[80:83], v[236:239], v[188:191], v[80:83]
	v_mfma_f32_16x16x32_bf16 v[68:71], v[228:231], v[220:223], v[68:71]
	v_mfma_f32_16x16x32_bf16 v[64:67], v[236:239], v[220:223], v[64:67]
	s_waitcnt lgkmcnt(0)
	v_mfma_f32_16x16x32_bf16 v[116:119], v[232:235], v[176:179], v[116:119]
	v_mfma_f32_16x16x32_bf16 v[112:115], v[240:243], v[176:179], v[112:115]
	v_mfma_f32_16x16x32_bf16 v[100:103], v[232:235], v[184:187], v[100:103]
	v_mfma_f32_16x16x32_bf16 v[96:99], v[240:243], v[184:187], v[96:99]
	v_mfma_f32_16x16x32_bf16 v[84:87], v[232:235], v[216:219], v[84:87]
	v_mfma_f32_16x16x32_bf16 v[80:83], v[240:243], v[216:219], v[80:83]
	v_mfma_f32_16x16x32_bf16 v[68:71], v[232:235], v[224:227], v[68:71]
	v_mfma_f32_16x16x32_bf16 v[64:67], v[240:243], v[224:227], v[64:67]
	s_setprio 0
	s_mov_b32 m0, s36
	v_lshl_add_u64 v[152:153], v[246:247], 0, s[66:67]
	s_barrier
	ds_read_b128 v[172:175], v155 offset:49152
	ds_read_b128 v[180:183], v155 offset:51200
	ds_read_b128 v[188:191], v155 offset:53248
	ds_read_b128 v[220:223], v155 offset:55296
	ds_read_b128 v[176:179], v155 offset:50176
	ds_read_b128 v[184:187], v155 offset:52224
	ds_read_b128 v[216:219], v155 offset:54272
	ds_read_b128 v[224:227], v155 offset:56320
	global_load_lds_dwordx4 v[152:153], off
	v_lshl_add_u64 v[152:153], v[248:249], 0, s[66:67]
	s_mov_b32 m0, s37
	s_nop 0
	global_load_lds_dwordx4 v[152:153], off
	s_barrier
	s_waitcnt lgkmcnt(4)
	s_setprio 1
	v_mfma_f32_16x16x32_bf16 v[60:63], v[156:159], v[172:175], v[60:63]
	v_mfma_f32_16x16x32_bf16 v[56:59], v[164:167], v[172:175], v[56:59]
	v_mfma_f32_16x16x32_bf16 v[44:47], v[156:159], v[180:183], v[44:47]
	v_mfma_f32_16x16x32_bf16 v[40:43], v[164:167], v[180:183], v[40:43]
	v_mfma_f32_16x16x32_bf16 v[28:31], v[156:159], v[188:191], v[28:31]
	v_mfma_f32_16x16x32_bf16 v[24:27], v[164:167], v[188:191], v[24:27]
	v_mfma_f32_16x16x32_bf16 v[12:15], v[156:159], v[220:223], v[12:15]
	v_mfma_f32_16x16x32_bf16 v[8:11], v[164:167], v[220:223], v[8:11]
	s_waitcnt lgkmcnt(0)
	v_mfma_f32_16x16x32_bf16 v[60:63], v[160:163], v[176:179], v[60:63]
	v_mfma_f32_16x16x32_bf16 v[56:59], v[168:171], v[176:179], v[56:59]
	v_mfma_f32_16x16x32_bf16 v[44:47], v[160:163], v[184:187], v[44:47]
	v_mfma_f32_16x16x32_bf16 v[40:43], v[168:171], v[184:187], v[40:43]
	v_mfma_f32_16x16x32_bf16 v[28:31], v[160:163], v[216:219], v[28:31]
	v_mfma_f32_16x16x32_bf16 v[24:27], v[168:171], v[216:219], v[24:27]
	v_mfma_f32_16x16x32_bf16 v[12:15], v[160:163], v[224:227], v[12:15]
	v_mfma_f32_16x16x32_bf16 v[8:11], v[168:171], v[224:227], v[8:11]
	s_setprio 0
	s_barrier
	s_add_u32 s22, s22, 0x40080
	s_addc_u32 s23, s23, 0
	s_add_i32 s24, s24, s29
	v_lshl_add_u64 v[152:153], s[22:23], 0, v[132:133]
	s_mov_b32 m0, s24
	s_nop 0
	global_load_lds_dwordx4 v[152:153], off
	v_lshl_add_u64 v[152:153], s[22:23], 0, v[128:129]
	s_add_i32 m0, s24, 0x2000
	s_nop 0
	global_load_lds_dwordx4 v[152:153], off
	s_waitcnt vmcnt(6)
	s_barrier
	s_setprio 1
	v_mfma_f32_16x16x32_bf16 v[52:55], v[228:231], v[172:175], v[52:55]
	v_mfma_f32_16x16x32_bf16 v[48:51], v[236:239], v[172:175], v[48:51]
	v_mfma_f32_16x16x32_bf16 v[36:39], v[228:231], v[180:183], v[36:39]
	v_mfma_f32_16x16x32_bf16 v[32:35], v[236:239], v[180:183], v[32:35]
	v_mfma_f32_16x16x32_bf16 v[20:23], v[228:231], v[188:191], v[20:23]
	v_mfma_f32_16x16x32_bf16 v[16:19], v[236:239], v[188:191], v[16:19]
	v_mfma_f32_16x16x32_bf16 v[4:7], v[228:231], v[220:223], v[4:7]
	v_mfma_f32_16x16x32_bf16 v[0:3], v[236:239], v[220:223], v[0:3]
	v_mfma_f32_16x16x32_bf16 v[52:55], v[232:235], v[176:179], v[52:55]
	v_mfma_f32_16x16x32_bf16 v[48:51], v[240:243], v[176:179], v[48:51]
	v_mfma_f32_16x16x32_bf16 v[36:39], v[232:235], v[184:187], v[36:39]
	v_mfma_f32_16x16x32_bf16 v[32:35], v[240:243], v[184:187], v[32:35]
	v_mfma_f32_16x16x32_bf16 v[20:23], v[232:235], v[216:219], v[20:23]
	v_mfma_f32_16x16x32_bf16 v[16:19], v[240:243], v[216:219], v[16:19]
	v_mfma_f32_16x16x32_bf16 v[4:7], v[232:235], v[224:227], v[4:7]
	v_mfma_f32_16x16x32_bf16 v[0:3], v[240:243], v[224:227], v[0:3]
	s_setprio 0
	s_add_i32 s46, s46, 2
	s_add_u32 s18, s18, 0x100
	s_addc_u32 s19, s19, 0
	s_add_u32 s44, s44, 0x100
	s_addc_u32 s45, s45, 0
	s_cmp_gt_u32 s46, 13
	s_barrier
	s_cbranch_scc0 .LBB0_1104
	v_mov_b32_e32 v153, v135
	s_mov_b64 s[18:19], s[0:1]
	s_load_dwordx2 s[18:19], s[18:19], 0x88
	s_nop 0
	v_readfirstlane_b32 s7, v153
	s_ashr_i32 s9, s7, 2
	s_lshr_b32 s7, s7, 1
	s_lshl_b32 s22, s41, 7
	s_and_b32 s7, s7, 0x60
	s_andn2_b32 s9, s9, 63
	s_or_b32 s7, s7, s22
	v_lshrrev_b32_e32 v152, 1, v153
	v_and_or_b32 v152, v152, 24, s7
	v_and_or_b32 v153, v153, 15, s9
	v_lshl_add_u32 v156, s16, 8, v153
	v_ashrrev_i32_e32 v153, 31, v152
	v_mov_b32_e32 v168, 0xbfb8aa3b
	v_mov_b32_e32 v169, 0xbfb8aa3b
	v_mov_b32_e32 v170, 1.0
	v_mov_b32_e32 v171, 1.0
	v_pk_mul_f32 v[160:161], v[124:125], v[168:169]
	v_pk_mul_f32 v[162:163], v[126:127], v[168:169]
	v_pk_mul_f32 v[164:165], v[116:117], v[168:169]
	v_pk_mul_f32 v[166:167], v[118:119], v[168:169]
	v_exp_f32_e32 v160, v160
	v_exp_f32_e32 v161, v161
	v_exp_f32_e32 v162, v162
	v_exp_f32_e32 v163, v163
	v_exp_f32_e32 v164, v164
	v_exp_f32_e32 v165, v165
	v_exp_f32_e32 v166, v166
	v_exp_f32_e32 v167, v167
	s_waitcnt lgkmcnt(0)
	v_lshl_add_u64 v[152:153], v[152:153], 1, s[18:19]
	s_mov_b64 s[18:19], 0xa2a4400
	v_lshl_add_u64 v[152:153], v[152:153], 0, s[18:19]
	s_and_b64 vcc, exec, s[4:5]
	s_mov_b32 s41, s6
	s_mov_b32 s16, s8
	s_mov_b64 s[22:23], s[12:13]
	v_pk_add_f32 v[160:161], v[160:161], v[170:171]
	v_pk_add_f32 v[162:163], v[162:163], v[170:171]
	v_pk_add_f32 v[164:165], v[164:165], v[170:171]
	v_pk_add_f32 v[166:167], v[166:167], v[170:171]
	v_rcp_f32_e32 v160, v160
	v_rcp_f32_e32 v161, v161
	v_rcp_f32_e32 v162, v162
	v_rcp_f32_e32 v163, v163
	v_rcp_f32_e32 v164, v164
	v_rcp_f32_e32 v165, v165
	v_rcp_f32_e32 v166, v166
	v_rcp_f32_e32 v167, v167
	v_mov_b32_e32 v158, v156
	v_mad_i64_i32 v[158:159], s[18:19], v158, s73, v[152:153]
	v_pk_mul_f32 v[124:125], v[124:125], v[160:161]
	v_pk_mul_f32 v[126:127], v[126:127], v[162:163]
	v_pk_mul_f32 v[116:117], v[116:117], v[164:165]
	v_pk_mul_f32 v[118:119], v[118:119], v[166:167]
	v_pk_mul_f32 v[120:121], v[120:121], v[124:125]
	v_pk_mul_f32 v[122:123], v[122:123], v[126:127]
	v_pk_mul_f32 v[112:113], v[112:113], v[116:117]
	v_pk_mul_f32 v[114:115], v[114:115], v[118:119]
	v_cvt_pk_bf16_f32 v120, v120, v121
	v_cvt_pk_bf16_f32 v121, v122, v123
	v_cvt_pk_bf16_f32 v122, v112, v113
	v_cvt_pk_bf16_f32 v123, v114, v115
	global_store_dwordx4 v[158:159], v[120:123], off sc1
	v_pk_mul_f32 v[160:161], v[108:109], v[168:169]
	v_pk_mul_f32 v[162:163], v[110:111], v[168:169]
	v_pk_mul_f32 v[164:165], v[100:101], v[168:169]
	v_pk_mul_f32 v[166:167], v[102:103], v[168:169]
	v_exp_f32_e32 v160, v160
	v_exp_f32_e32 v161, v161
	v_exp_f32_e32 v162, v162
	v_exp_f32_e32 v163, v163
	v_exp_f32_e32 v164, v164
	v_exp_f32_e32 v165, v165
	v_exp_f32_e32 v166, v166
	v_exp_f32_e32 v167, v167
	v_pk_add_f32 v[160:161], v[160:161], v[170:171]
	v_pk_add_f32 v[162:163], v[162:163], v[170:171]
	v_pk_add_f32 v[164:165], v[164:165], v[170:171]
	v_pk_add_f32 v[166:167], v[166:167], v[170:171]
	v_rcp_f32_e32 v160, v160
	v_rcp_f32_e32 v161, v161
	v_rcp_f32_e32 v162, v162
	v_rcp_f32_e32 v163, v163
	v_rcp_f32_e32 v164, v164
	v_rcp_f32_e32 v165, v165
	v_rcp_f32_e32 v166, v166
	v_rcp_f32_e32 v167, v167
	v_add_u32_e32 v158, 0x10, v156
	v_mad_i64_i32 v[158:159], s[18:19], v158, s73, v[152:153]
	v_pk_mul_f32 v[108:109], v[108:109], v[160:161]
	v_pk_mul_f32 v[110:111], v[110:111], v[162:163]
	v_pk_mul_f32 v[100:101], v[100:101], v[164:165]
	v_pk_mul_f32 v[102:103], v[102:103], v[166:167]
	v_pk_mul_f32 v[104:105], v[104:105], v[108:109]
	v_pk_mul_f32 v[106:107], v[106:107], v[110:111]
	v_pk_mul_f32 v[96:97], v[96:97], v[100:101]
	v_pk_mul_f32 v[98:99], v[98:99], v[102:103]
	v_cvt_pk_bf16_f32 v104, v104, v105
	v_cvt_pk_bf16_f32 v105, v106, v107
	v_cvt_pk_bf16_f32 v106, v96, v97
	v_cvt_pk_bf16_f32 v107, v98, v99
	global_store_dwordx4 v[158:159], v[104:107], off sc1
	v_pk_mul_f32 v[160:161], v[92:93], v[168:169]
	v_pk_mul_f32 v[162:163], v[94:95], v[168:169]
	v_pk_mul_f32 v[164:165], v[84:85], v[168:169]
	v_pk_mul_f32 v[166:167], v[86:87], v[168:169]
	v_exp_f32_e32 v160, v160
	v_exp_f32_e32 v161, v161
	v_exp_f32_e32 v162, v162
	v_exp_f32_e32 v163, v163
	v_exp_f32_e32 v164, v164
	v_exp_f32_e32 v165, v165
	v_exp_f32_e32 v166, v166
	v_exp_f32_e32 v167, v167
	v_pk_add_f32 v[160:161], v[160:161], v[170:171]
	v_pk_add_f32 v[162:163], v[162:163], v[170:171]
	v_pk_add_f32 v[164:165], v[164:165], v[170:171]
	v_pk_add_f32 v[166:167], v[166:167], v[170:171]
	v_rcp_f32_e32 v160, v160
	v_rcp_f32_e32 v161, v161
	v_rcp_f32_e32 v162, v162
	v_rcp_f32_e32 v163, v163
	v_rcp_f32_e32 v164, v164
	v_rcp_f32_e32 v165, v165
	v_rcp_f32_e32 v166, v166
	v_rcp_f32_e32 v167, v167
	v_add_u32_e32 v158, 0x20, v156
	v_mad_i64_i32 v[158:159], s[18:19], v158, s73, v[152:153]
	v_pk_mul_f32 v[92:93], v[92:93], v[160:161]
	v_pk_mul_f32 v[94:95], v[94:95], v[162:163]
	v_pk_mul_f32 v[84:85], v[84:85], v[164:165]
	v_pk_mul_f32 v[86:87], v[86:87], v[166:167]
	v_pk_mul_f32 v[88:89], v[88:89], v[92:93]
	v_pk_mul_f32 v[90:91], v[90:91], v[94:95]
	v_pk_mul_f32 v[80:81], v[80:81], v[84:85]
	v_pk_mul_f32 v[82:83], v[82:83], v[86:87]
	v_cvt_pk_bf16_f32 v88, v88, v89
	v_cvt_pk_bf16_f32 v89, v90, v91
	v_cvt_pk_bf16_f32 v90, v80, v81
	v_cvt_pk_bf16_f32 v91, v82, v83
	global_store_dwordx4 v[158:159], v[88:91], off sc1
	v_pk_mul_f32 v[160:161], v[76:77], v[168:169]
	v_pk_mul_f32 v[162:163], v[78:79], v[168:169]
	v_pk_mul_f32 v[164:165], v[68:69], v[168:169]
	v_pk_mul_f32 v[166:167], v[70:71], v[168:169]
	v_exp_f32_e32 v160, v160
	v_exp_f32_e32 v161, v161
	v_exp_f32_e32 v162, v162
	v_exp_f32_e32 v163, v163
	v_exp_f32_e32 v164, v164
	v_exp_f32_e32 v165, v165
	v_exp_f32_e32 v166, v166
	v_exp_f32_e32 v167, v167
	v_pk_add_f32 v[160:161], v[160:161], v[170:171]
	v_pk_add_f32 v[162:163], v[162:163], v[170:171]
	v_pk_add_f32 v[164:165], v[164:165], v[170:171]
	v_pk_add_f32 v[166:167], v[166:167], v[170:171]
	v_rcp_f32_e32 v160, v160
	v_rcp_f32_e32 v161, v161
	v_rcp_f32_e32 v162, v162
	v_rcp_f32_e32 v163, v163
	v_rcp_f32_e32 v164, v164
	v_rcp_f32_e32 v165, v165
	v_rcp_f32_e32 v166, v166
	v_rcp_f32_e32 v167, v167
	v_add_u32_e32 v158, 0x30, v156
	v_mad_i64_i32 v[158:159], s[18:19], v158, s73, v[152:153]
	v_pk_mul_f32 v[76:77], v[76:77], v[160:161]
	v_pk_mul_f32 v[78:79], v[78:79], v[162:163]
	v_pk_mul_f32 v[68:69], v[68:69], v[164:165]
	v_pk_mul_f32 v[70:71], v[70:71], v[166:167]
	v_pk_mul_f32 v[72:73], v[72:73], v[76:77]
	v_pk_mul_f32 v[74:75], v[74:75], v[78:79]
	v_pk_mul_f32 v[64:65], v[64:65], v[68:69]
	v_pk_mul_f32 v[66:67], v[66:67], v[70:71]
	v_cvt_pk_bf16_f32 v72, v72, v73
	v_cvt_pk_bf16_f32 v73, v74, v75
	v_cvt_pk_bf16_f32 v74, v64, v65
	v_cvt_pk_bf16_f32 v75, v66, v67
	global_store_dwordx4 v[158:159], v[72:75], off sc1
	v_pk_mul_f32 v[160:161], v[60:61], v[168:169]
	v_pk_mul_f32 v[162:163], v[62:63], v[168:169]
	v_pk_mul_f32 v[164:165], v[52:53], v[168:169]
	v_pk_mul_f32 v[166:167], v[54:55], v[168:169]
	v_exp_f32_e32 v160, v160
	v_exp_f32_e32 v161, v161
	v_exp_f32_e32 v162, v162
	v_exp_f32_e32 v163, v163
	v_exp_f32_e32 v164, v164
	v_exp_f32_e32 v165, v165
	v_exp_f32_e32 v166, v166
	v_exp_f32_e32 v167, v167
	v_pk_add_f32 v[160:161], v[160:161], v[170:171]
	v_pk_add_f32 v[162:163], v[162:163], v[170:171]
	v_pk_add_f32 v[164:165], v[164:165], v[170:171]
	v_pk_add_f32 v[166:167], v[166:167], v[170:171]
	v_rcp_f32_e32 v160, v160
	v_rcp_f32_e32 v161, v161
	v_rcp_f32_e32 v162, v162
	v_rcp_f32_e32 v163, v163
	v_rcp_f32_e32 v164, v164
	v_rcp_f32_e32 v165, v165
	v_rcp_f32_e32 v166, v166
	v_rcp_f32_e32 v167, v167
	v_add_u32_e32 v158, 0x80, v156
	v_mad_i64_i32 v[158:159], s[18:19], v158, s73, v[152:153]
	v_pk_mul_f32 v[60:61], v[60:61], v[160:161]
	v_pk_mul_f32 v[62:63], v[62:63], v[162:163]
	v_pk_mul_f32 v[52:53], v[52:53], v[164:165]
	v_pk_mul_f32 v[54:55], v[54:55], v[166:167]
	v_pk_mul_f32 v[56:57], v[56:57], v[60:61]
	v_pk_mul_f32 v[58:59], v[58:59], v[62:63]
	v_pk_mul_f32 v[48:49], v[48:49], v[52:53]
	v_pk_mul_f32 v[50:51], v[50:51], v[54:55]
	v_cvt_pk_bf16_f32 v56, v56, v57
	v_cvt_pk_bf16_f32 v57, v58, v59
	v_cvt_pk_bf16_f32 v58, v48, v49
	v_cvt_pk_bf16_f32 v59, v50, v51
	global_store_dwordx4 v[158:159], v[56:59], off sc1
	v_pk_mul_f32 v[160:161], v[44:45], v[168:169]
	v_pk_mul_f32 v[162:163], v[46:47], v[168:169]
	v_pk_mul_f32 v[164:165], v[36:37], v[168:169]
	v_pk_mul_f32 v[166:167], v[38:39], v[168:169]
	v_exp_f32_e32 v160, v160
	v_exp_f32_e32 v161, v161
	v_exp_f32_e32 v162, v162
	v_exp_f32_e32 v163, v163
	v_exp_f32_e32 v164, v164
	v_exp_f32_e32 v165, v165
	v_exp_f32_e32 v166, v166
	v_exp_f32_e32 v167, v167
	v_pk_add_f32 v[160:161], v[160:161], v[170:171]
	v_pk_add_f32 v[162:163], v[162:163], v[170:171]
	v_pk_add_f32 v[164:165], v[164:165], v[170:171]
	v_pk_add_f32 v[166:167], v[166:167], v[170:171]
	v_rcp_f32_e32 v160, v160
	v_rcp_f32_e32 v161, v161
	v_rcp_f32_e32 v162, v162
	v_rcp_f32_e32 v163, v163
	v_rcp_f32_e32 v164, v164
	v_rcp_f32_e32 v165, v165
	v_rcp_f32_e32 v166, v166
	v_rcp_f32_e32 v167, v167
	v_add_u32_e32 v158, 0x90, v156
	v_mad_i64_i32 v[158:159], s[18:19], v158, s73, v[152:153]
	v_pk_mul_f32 v[44:45], v[44:45], v[160:161]
	v_pk_mul_f32 v[46:47], v[46:47], v[162:163]
	v_pk_mul_f32 v[36:37], v[36:37], v[164:165]
	v_pk_mul_f32 v[38:39], v[38:39], v[166:167]
	v_pk_mul_f32 v[40:41], v[40:41], v[44:45]
	v_pk_mul_f32 v[42:43], v[42:43], v[46:47]
	v_pk_mul_f32 v[32:33], v[32:33], v[36:37]
	v_pk_mul_f32 v[34:35], v[34:35], v[38:39]
	v_cvt_pk_bf16_f32 v40, v40, v41
	v_cvt_pk_bf16_f32 v41, v42, v43
	v_cvt_pk_bf16_f32 v42, v32, v33
	v_cvt_pk_bf16_f32 v43, v34, v35
	global_store_dwordx4 v[158:159], v[40:43], off sc1
	v_pk_mul_f32 v[160:161], v[28:29], v[168:169]
	v_pk_mul_f32 v[162:163], v[30:31], v[168:169]
	v_pk_mul_f32 v[164:165], v[20:21], v[168:169]
	v_pk_mul_f32 v[166:167], v[22:23], v[168:169]
	v_exp_f32_e32 v160, v160
	v_exp_f32_e32 v161, v161
	v_exp_f32_e32 v162, v162
	v_exp_f32_e32 v163, v163
	v_exp_f32_e32 v164, v164
	v_exp_f32_e32 v165, v165
	v_exp_f32_e32 v166, v166
	v_exp_f32_e32 v167, v167
	v_pk_add_f32 v[160:161], v[160:161], v[170:171]
	v_pk_add_f32 v[162:163], v[162:163], v[170:171]
	v_pk_add_f32 v[164:165], v[164:165], v[170:171]
	v_pk_add_f32 v[166:167], v[166:167], v[170:171]
	v_rcp_f32_e32 v160, v160
	v_rcp_f32_e32 v161, v161
	v_rcp_f32_e32 v162, v162
	v_rcp_f32_e32 v163, v163
	v_rcp_f32_e32 v164, v164
	v_rcp_f32_e32 v165, v165
	v_rcp_f32_e32 v166, v166
	v_rcp_f32_e32 v167, v167
	v_add_u32_e32 v158, 0xa0, v156
	v_mad_i64_i32 v[158:159], s[18:19], v158, s73, v[152:153]
	v_pk_mul_f32 v[28:29], v[28:29], v[160:161]
	v_pk_mul_f32 v[30:31], v[30:31], v[162:163]
	v_pk_mul_f32 v[20:21], v[20:21], v[164:165]
	v_pk_mul_f32 v[22:23], v[22:23], v[166:167]
	v_pk_mul_f32 v[24:25], v[24:25], v[28:29]
	v_pk_mul_f32 v[26:27], v[26:27], v[30:31]
	v_pk_mul_f32 v[16:17], v[16:17], v[20:21]
	v_pk_mul_f32 v[18:19], v[18:19], v[22:23]
	v_cvt_pk_bf16_f32 v24, v24, v25
	v_cvt_pk_bf16_f32 v25, v26, v27
	v_cvt_pk_bf16_f32 v26, v16, v17
	v_cvt_pk_bf16_f32 v27, v18, v19
	global_store_dwordx4 v[158:159], v[24:27], off sc1
	v_pk_mul_f32 v[160:161], v[12:13], v[168:169]
	v_pk_mul_f32 v[162:163], v[14:15], v[168:169]
	v_pk_mul_f32 v[164:165], v[4:5], v[168:169]
	v_pk_mul_f32 v[166:167], v[6:7], v[168:169]
	v_exp_f32_e32 v160, v160
	v_exp_f32_e32 v161, v161
	v_exp_f32_e32 v162, v162
	v_exp_f32_e32 v163, v163
	v_exp_f32_e32 v164, v164
	v_exp_f32_e32 v165, v165
	v_exp_f32_e32 v166, v166
	v_exp_f32_e32 v167, v167
	v_pk_add_f32 v[160:161], v[160:161], v[170:171]
	v_pk_add_f32 v[162:163], v[162:163], v[170:171]
	v_pk_add_f32 v[164:165], v[164:165], v[170:171]
	v_pk_add_f32 v[166:167], v[166:167], v[170:171]
	v_rcp_f32_e32 v160, v160
	v_rcp_f32_e32 v161, v161
	v_rcp_f32_e32 v162, v162
	v_rcp_f32_e32 v163, v163
	v_rcp_f32_e32 v164, v164
	v_rcp_f32_e32 v165, v165
	v_rcp_f32_e32 v166, v166
	v_rcp_f32_e32 v167, v167
	v_add_u32_e32 v158, 0xb0, v156
	v_mad_i64_i32 v[158:159], s[18:19], v158, s73, v[152:153]
	v_pk_mul_f32 v[12:13], v[12:13], v[160:161]
	v_pk_mul_f32 v[14:15], v[14:15], v[162:163]
	v_pk_mul_f32 v[4:5], v[4:5], v[164:165]
	v_pk_mul_f32 v[6:7], v[6:7], v[166:167]
	v_pk_mul_f32 v[8:9], v[8:9], v[12:13]
	v_pk_mul_f32 v[10:11], v[10:11], v[14:15]
	v_pk_mul_f32 v[0:1], v[0:1], v[4:5]
	v_pk_mul_f32 v[2:3], v[2:3], v[6:7]
	v_cvt_pk_bf16_f32 v8, v8, v9
	v_cvt_pk_bf16_f32 v9, v10, v11
	v_cvt_pk_bf16_f32 v10, v0, v1
	v_cvt_pk_bf16_f32 v11, v2, v3
	global_store_dwordx4 v[158:159], v[8:11], off sc1
	s_mov_b64 s[18:19], s[10:11]
	s_cbranch_vccz .LBB0_1101
	s_waitcnt vmcnt(0)
	s_cmpk_gt_u32 s14, 0xff
	s_cbranch_scc1 .LBB0_1108
	s_barrier

.LBB0_1233:
	s_add_u32 s8, s12, 0x80
	s_addc_u32 s9, s13, 0
	s_add_u32 s38, s10, 0x100
	v_mov_b32_e32 v0, 0
	s_addc_u32 s39, s11, 0
	s_mov_b32 s10, 0
	v_mov_b32_e32 v1, v0
	v_mov_b64_e32 v[2:3], 0
	v_mov_b64_e32 v[4:5], 0
	v_mov_b64_e32 v[6:7], 0
	v_mov_b64_e32 v[8:9], 0
	v_mov_b64_e32 v[10:11], 0
	v_mov_b64_e32 v[12:13], 0
	v_mov_b64_e32 v[14:15], 0
	v_mov_b64_e32 v[16:17], 0
	v_mov_b64_e32 v[18:19], 0
	v_mov_b64_e32 v[20:21], 0
	v_mov_b64_e32 v[22:23], 0
	v_mov_b64_e32 v[24:25], 0
	v_mov_b64_e32 v[26:27], 0
	v_mov_b64_e32 v[28:29], 0
	v_mov_b64_e32 v[30:31], 0
	v_mov_b64_e32 v[32:33], 0
	v_mov_b64_e32 v[34:35], 0
	v_mov_b64_e32 v[36:37], 0
	v_mov_b64_e32 v[38:39], 0
	v_mov_b64_e32 v[40:41], 0
	v_mov_b64_e32 v[42:43], 0
	v_mov_b64_e32 v[44:45], 0
	v_mov_b64_e32 v[46:47], 0
	v_mov_b64_e32 v[48:49], 0
	v_mov_b64_e32 v[50:51], 0
	v_mov_b64_e32 v[52:53], 0
	v_mov_b64_e32 v[54:55], 0
	v_mov_b64_e32 v[56:57], 0
	v_mov_b64_e32 v[58:59], 0
	v_mov_b64_e32 v[60:61], 0
	v_mov_b64_e32 v[62:63], 0
	v_mov_b64_e32 v[64:65], 0
	v_mov_b64_e32 v[66:67], 0
	v_mov_b64_e32 v[68:69], 0
	v_mov_b64_e32 v[70:71], 0
	v_mov_b64_e32 v[72:73], 0
	v_mov_b64_e32 v[74:75], 0
	v_mov_b64_e32 v[76:77], 0
	v_mov_b64_e32 v[78:79], 0
	v_mov_b64_e32 v[80:81], 0
	v_mov_b64_e32 v[82:83], 0
	v_mov_b64_e32 v[84:85], 0
	v_mov_b64_e32 v[86:87], 0
	v_mov_b64_e32 v[88:89], 0
	v_mov_b64_e32 v[90:91], 0
	v_mov_b64_e32 v[92:93], 0
	v_mov_b64_e32 v[94:95], 0
	v_mov_b64_e32 v[96:97], 0
	v_mov_b64_e32 v[98:99], 0
	v_mov_b64_e32 v[100:101], 0
	v_mov_b64_e32 v[102:103], 0
	v_mov_b64_e32 v[104:105], 0
	v_mov_b64_e32 v[106:107], 0
	v_mov_b64_e32 v[108:109], 0
	v_mov_b64_e32 v[110:111], 0
	v_mov_b64_e32 v[112:113], 0
	v_mov_b64_e32 v[114:115], 0
	v_mov_b64_e32 v[116:117], 0
	v_mov_b64_e32 v[118:119], 0
	v_mov_b64_e32 v[120:121], 0
	v_mov_b64_e32 v[122:123], 0
	v_mov_b64_e32 v[124:125], 0
	v_mov_b64_e32 v[126:127], 0
